# prep MWt jobs: per-element LDS read->wait->fmac chains batched (12 LDS reads per iteration issued together, one wait)
# speedup vs baseline: 1.0066x; 1.0066x over previous
.LBB0_55:
	v_add_u32_e32 v17, s0, v4
	ds_read2_b32 v[18:19], v17 offset1:32
	s_addk_i32 s0, 0x400
	s_cmpk_eq_i32 s0, 0x2000
	v_add_u32_e32 v20, v2, v5
	v_and_b32_e32 v21, 56, v20
	v_lshlrev_b32_e32 v22, 2, v21
	ds_read_b32 v23, v22 offset:8192
	v_add_u32_e32 v24, v0, v5
	v_and_b32_e32 v25, 48, v24
	v_lshlrev_b32_e32 v26, 2, v25
	ds_read_b32 v27, v26 offset:8192
	ds_read2_b32 v[28:29], v17 offset0:64 offset1:96
	v_add_u32_e32 v30, v6, v5
	v_and_b32_e32 v31, 56, v30
	v_lshlrev_b32_e32 v33, 2, v31
	ds_read_b32 v34, v33 offset:8192
	v_add_u32_e32 v35, v7, v5
	v_and_b32_e32 v36, 32, v35
	v_lshlrev_b32_e32 v37, 2, v36
	ds_read_b32 v38, v37 offset:8192
	ds_read2_b32 v[40:41], v17 offset0:128 offset1:160
	v_add_u32_e32 v39, v8, v5
	v_and_b32_e32 v42, 56, v39
	v_lshlrev_b32_e32 v43, 2, v42
	ds_read_b32 v44, v43 offset:8192
	v_add_u32_e32 v45, v9, v5
	v_and_b32_e32 v46, 48, v45
	v_lshlrev_b32_e32 v47, 2, v46
	ds_read_b32 v48, v47 offset:8192
	ds_read2_b32 v[50:51], v17 offset0:192 offset1:224
	v_add_u32_e32 v49, v10, v5
	v_and_b32_e32 v52, 56, v49
	v_lshlrev_b32_e32 v53, 2, v52
	ds_read_b32 v54, v53 offset:8192
	v_add_u32_e32 v5, v5, v11
	s_waitcnt lgkmcnt(0)
	v_fmac_f32_e32 v3, v12, v18
	v_fmac_f32_e32 v3, v23, v19
	v_fmac_f32_e32 v3, v27, v28
	v_fmac_f32_e32 v3, v34, v29
	v_fmac_f32_e32 v3, v38, v40
	v_fmac_f32_e32 v3, v44, v41
	v_fmac_f32_e32 v3, v48, v50
	v_fmac_f32_e32 v3, v54, v51
	s_cbranch_scc0 .LBB0_55
	v_or_b32_e32 v12, 1, v2
	v_add_u32_e32 v13, 8, v11
	v_add_u32_e32 v14, 2, v0
	v_add_u32_e32 v15, 3, v6
	v_add_u32_e32 v16, 4, v7
	v_add_u32_e32 v17, 5, v8
	v_add_u32_e32 v18, 6, v9
	v_add_u32_e32 v19, 7, v10
	v_mov_b32_e32 v5, 0
	v_mov_b32_e32 v20, 0
	s_mov_b32 s0, 0
.LBB0_57:
	v_and_b32_e32 v25, 56, v20
	v_lshlrev_b32_e32 v26, 2, v25
	v_add_u32_e32 v27, s0, v4
	ds_read_b32 v28, v26 offset:8192
	ds_read2_b32 v[30:31], v27 offset1:32
	s_addk_i32 s0, 0x400
	s_cmpk_lg_i32 s0, 0x2000
	v_add_u32_e32 v29, v12, v20
	v_and_b32_e32 v33, 57, v29
	v_lshlrev_b32_e32 v34, 2, v33
	ds_read_b32 v35, v34 offset:8192
	v_add_u32_e32 v36, v14, v20
	v_and_b32_e32 v37, 58, v36
	v_lshlrev_b32_e32 v38, 2, v37
	ds_read_b32 v39, v38 offset:8192
	ds_read2_b32 v[40:41], v27 offset0:64 offset1:96
	v_add_u32_e32 v42, v15, v20
	v_and_b32_e32 v43, 59, v42
	v_lshlrev_b32_e32 v44, 2, v43
	ds_read_b32 v45, v44 offset:8192
	v_add_u32_e32 v46, v16, v20
	v_and_b32_e32 v47, 60, v46
	v_lshlrev_b32_e32 v48, 2, v47
	ds_read_b32 v49, v48 offset:8192
	ds_read2_b32 v[50:51], v27 offset0:128 offset1:160
	v_add_u32_e32 v52, v17, v20
	v_and_b32_e32 v53, 61, v52
	v_lshlrev_b32_e32 v54, 2, v53
	ds_read_b32 v55, v54 offset:8192
	v_add_u32_e32 v56, v18, v20
	v_and_b32_e32 v57, 62, v56
	v_lshlrev_b32_e32 v58, 2, v57
	ds_read_b32 v59, v58 offset:8192
	ds_read2_b32 v[60:61], v27 offset0:192 offset1:224
	v_add_u32_e32 v62, v19, v20
	v_and_b32_e32 v63, 63, v62
	v_lshlrev_b32_e32 v64, 2, v63
	ds_read_b32 v65, v64 offset:8192
	v_add_u32_e32 v20, v20, v13
	s_waitcnt lgkmcnt(0)
	v_fmac_f32_e32 v5, v28, v30
	v_fmac_f32_e32 v5, v35, v31
	v_fmac_f32_e32 v5, v39, v40
	v_fmac_f32_e32 v5, v45, v41
	v_fmac_f32_e32 v5, v49, v50
	v_fmac_f32_e32 v5, v55, v51
	v_fmac_f32_e32 v5, v59, v60
	v_fmac_f32_e32 v5, v65, v61
	s_cbranch_scc1 .LBB0_57
	v_or_b32_e32 v13, 2, v2
	v_add_u32_e32 v14, 16, v11
	v_add_u32_e32 v15, 4, v0
	v_add_u32_e32 v16, 6, v6
	v_add_u32_e32 v17, 8, v7
	v_add_u32_e32 v18, 10, v8
	v_add_u32_e32 v19, 12, v9
	v_add_u32_e32 v20, 14, v10
	v_mov_b32_e32 v12, 0
	v_mov_b32_e32 v21, 0
	s_mov_b32 s0, 0
.LBB0_59:
	v_and_b32_e32 v26, 48, v21
	v_lshlrev_b32_e32 v27, 2, v26
	v_add_u32_e32 v28, s0, v4
	ds_read_b32 v29, v27 offset:8192
	ds_read2_b32 v[30:31], v28 offset1:32
	s_addk_i32 s0, 0x400
	s_cmpk_lg_i32 s0, 0x2000
	v_add_u32_e32 v33, v13, v21
	v_and_b32_e32 v34, 58, v33
	v_lshlrev_b32_e32 v35, 2, v34
	ds_read_b32 v36, v35 offset:8192
	v_add_u32_e32 v37, v15, v21
	v_and_b32_e32 v38, 52, v37
	v_lshlrev_b32_e32 v39, 2, v38
	ds_read_b32 v40, v39 offset:8192
	ds_read2_b32 v[42:43], v28 offset0:64 offset1:96
	v_add_u32_e32 v41, v16, v21
	v_and_b32_e32 v44, 62, v41
	v_lshlrev_b32_e32 v45, 2, v44
	ds_read_b32 v46, v45 offset:8192
	v_add_u32_e32 v47, v17, v21
	v_and_b32_e32 v48, 56, v47
	v_lshlrev_b32_e32 v49, 2, v48
	ds_read_b32 v50, v49 offset:8192
	ds_read2_b32 v[52:53], v28 offset0:128 offset1:160
	v_add_u32_e32 v51, v18, v21
	v_and_b32_e32 v54, 58, v51
	v_lshlrev_b32_e32 v55, 2, v54
	ds_read_b32 v56, v55 offset:8192
	v_add_u32_e32 v57, v19, v21
	v_and_b32_e32 v58, 60, v57
	v_lshlrev_b32_e32 v59, 2, v58
	ds_read_b32 v60, v59 offset:8192
	ds_read2_b32 v[62:63], v28 offset0:192 offset1:224
	v_add_u32_e32 v61, v20, v21
	v_and_b32_e32 v64, 62, v61
	v_lshlrev_b32_e32 v65, 2, v64
	ds_read_b32 v66, v65 offset:8192
	v_add_u32_e32 v21, v21, v14
	s_waitcnt lgkmcnt(0)
	v_fmac_f32_e32 v12, v29, v30
	v_fmac_f32_e32 v12, v36, v31
	v_fmac_f32_e32 v12, v40, v42
	v_fmac_f32_e32 v12, v46, v43
	v_fmac_f32_e32 v12, v50, v52
	v_fmac_f32_e32 v12, v56, v53
	v_fmac_f32_e32 v12, v60, v62
	v_fmac_f32_e32 v12, v66, v63
	s_cbranch_scc1 .LBB0_59
	v_or_b32_e32 v14, 3, v2
	v_add_u32_e32 v15, 24, v11
	v_add_u32_e32 v16, 6, v0
	v_add_u32_e32 v17, 9, v6
	v_add_u32_e32 v18, 12, v7
	v_add_u32_e32 v19, 15, v8
	v_add_u32_e32 v20, 18, v9
	v_add_u32_e32 v21, 21, v10
	v_mov_b32_e32 v13, 0
	v_mov_b32_e32 v22, 0
	s_mov_b32 s0, 0
.LBB0_61:
	v_and_b32_e32 v27, 56, v22
	v_lshlrev_b32_e32 v28, 2, v27
	v_add_u32_e32 v29, s0, v4
	ds_read_b32 v30, v28 offset:8192
	ds_read2_b32 v[34:35], v29 offset1:32
	s_addk_i32 s0, 0x400
	s_cmpk_lg_i32 s0, 0x2000
	v_add_u32_e32 v31, v14, v22
	v_and_b32_e32 v33, 59, v31
	v_lshlrev_b32_e32 v36, 2, v33
	ds_read_b32 v37, v36 offset:8192
	v_add_u32_e32 v38, v16, v22
	v_and_b32_e32 v39, 62, v38
	v_lshlrev_b32_e32 v40, 2, v39
	ds_read_b32 v41, v40 offset:8192
	ds_read2_b32 v[42:43], v29 offset0:64 offset1:96
	v_add_u32_e32 v44, v17, v22
	v_and_b32_e32 v45, 57, v44
	v_lshlrev_b32_e32 v46, 2, v45
	ds_read_b32 v47, v46 offset:8192
	v_add_u32_e32 v48, v18, v22
	v_and_b32_e32 v49, 60, v48
	v_lshlrev_b32_e32 v50, 2, v49
	ds_read_b32 v51, v50 offset:8192
	ds_read2_b32 v[52:53], v29 offset0:128 offset1:160
	v_add_u32_e32 v54, v19, v22
	v_and_b32_e32 v55, 63, v54
	v_lshlrev_b32_e32 v56, 2, v55
	ds_read_b32 v57, v56 offset:8192
	v_add_u32_e32 v58, v20, v22
	v_and_b32_e32 v59, 58, v58
	v_lshlrev_b32_e32 v60, 2, v59
	ds_read_b32 v61, v60 offset:8192
	ds_read2_b32 v[62:63], v29 offset0:192 offset1:224
	v_add_u32_e32 v64, v21, v22
	v_and_b32_e32 v65, 61, v64
	v_lshlrev_b32_e32 v66, 2, v65
	ds_read_b32 v67, v66 offset:8192
	v_add_u32_e32 v22, v22, v15
	s_waitcnt lgkmcnt(0)
	v_fmac_f32_e32 v13, v30, v34
	v_fmac_f32_e32 v13, v37, v35
	v_fmac_f32_e32 v13, v41, v42
	v_fmac_f32_e32 v13, v47, v43
	v_fmac_f32_e32 v13, v51, v52
	v_fmac_f32_e32 v13, v57, v53
	v_fmac_f32_e32 v13, v61, v62
	v_fmac_f32_e32 v13, v67, v63
	s_cbranch_scc1 .LBB0_61
	v_or_b32_e32 v15, 4, v2
	v_add_u32_e32 v16, 32, v11
	v_add_u32_e32 v17, 8, v0
	v_add_u32_e32 v18, 12, v6
	v_add_u32_e32 v19, 16, v7
	v_add_u32_e32 v20, 20, v8
	v_add_u32_e32 v21, 24, v9
	v_add_u32_e32 v22, 28, v10
	v_mov_b32_e32 v14, 0
	v_mov_b32_e32 v23, 0
	s_mov_b32 s0, 0
.LBB0_63:
	v_and_b32_e32 v28, 32, v23
	v_lshlrev_b32_e32 v29, 2, v28
	v_add_u32_e32 v30, s0, v4
	ds_read_b32 v31, v29 offset:8192
	ds_read2_b32 v[34:35], v30 offset1:32
	s_addk_i32 s0, 0x400
	s_cmpk_lg_i32 s0, 0x2000
	v_add_u32_e32 v33, v15, v23
	v_and_b32_e32 v36, 60, v33
	v_lshlrev_b32_e32 v37, 2, v36
	ds_read_b32 v38, v37 offset:8192
	v_add_u32_e32 v39, v17, v23
	v_and_b32_e32 v40, 56, v39
	v_lshlrev_b32_e32 v41, 2, v40
	ds_read_b32 v42, v41 offset:8192
	ds_read2_b32 v[44:45], v30 offset0:64 offset1:96
	v_add_u32_e32 v43, v18, v23
	v_and_b32_e32 v46, 60, v43
	v_lshlrev_b32_e32 v47, 2, v46
	ds_read_b32 v48, v47 offset:8192
	v_add_u32_e32 v49, v19, v23
	v_and_b32_e32 v50, 48, v49
	v_lshlrev_b32_e32 v51, 2, v50
	ds_read_b32 v52, v51 offset:8192
	ds_read2_b32 v[54:55], v30 offset0:128 offset1:160
	v_add_u32_e32 v53, v20, v23
	v_and_b32_e32 v56, 60, v53
	v_lshlrev_b32_e32 v57, 2, v56
	ds_read_b32 v58, v57 offset:8192
	v_add_u32_e32 v59, v21, v23
	v_and_b32_e32 v60, 56, v59
	v_lshlrev_b32_e32 v61, 2, v60
	ds_read_b32 v62, v61 offset:8192
	ds_read2_b32 v[64:65], v30 offset0:192 offset1:224
	v_add_u32_e32 v63, v22, v23
	v_and_b32_e32 v66, 60, v63
	v_lshlrev_b32_e32 v67, 2, v66
	ds_read_b32 v68, v67 offset:8192
	v_add_u32_e32 v23, v23, v16
	s_waitcnt lgkmcnt(0)
	v_fmac_f32_e32 v14, v31, v34
	v_fmac_f32_e32 v14, v38, v35
	v_fmac_f32_e32 v14, v42, v44
	v_fmac_f32_e32 v14, v48, v45
	v_fmac_f32_e32 v14, v52, v54
	v_fmac_f32_e32 v14, v58, v55
	v_fmac_f32_e32 v14, v62, v64
	v_fmac_f32_e32 v14, v68, v65
	s_cbranch_scc1 .LBB0_63
	v_or_b32_e32 v16, 5, v2
	v_add_u32_e32 v17, 40, v11
	v_add_u32_e32 v18, 10, v0
	v_add_u32_e32 v19, 15, v6
	v_add_u32_e32 v20, 20, v7
	v_add_u32_e32 v21, 25, v8
	v_add_u32_e32 v22, 30, v9
	v_add_u32_e32 v23, 35, v10
	v_mov_b32_e32 v15, 0
	v_mov_b32_e32 v24, 0
	s_mov_b32 s0, 0
.LBB0_65:
	v_and_b32_e32 v29, 56, v24
	v_lshlrev_b32_e32 v30, 2, v29
	v_add_u32_e32 v31, s0, v4
	ds_read_b32 v33, v30 offset:8192
	ds_read2_b32 v[34:35], v31 offset1:32
	s_addk_i32 s0, 0x400
	s_cmpk_lg_i32 s0, 0x2000
	v_add_u32_e32 v36, v16, v24
	v_and_b32_e32 v37, 61, v36
	v_lshlrev_b32_e32 v38, 2, v37
	ds_read_b32 v39, v38 offset:8192
	v_add_u32_e32 v40, v18, v24
	v_and_b32_e32 v41, 58, v40
	v_lshlrev_b32_e32 v42, 2, v41
	ds_read_b32 v43, v42 offset:8192
	ds_read2_b32 v[44:45], v31 offset0:64 offset1:96
	v_add_u32_e32 v46, v19, v24
	v_and_b32_e32 v47, 63, v46
	v_lshlrev_b32_e32 v48, 2, v47
	ds_read_b32 v49, v48 offset:8192
	v_add_u32_e32 v50, v20, v24
	v_and_b32_e32 v51, 60, v50
	v_lshlrev_b32_e32 v52, 2, v51
	ds_read_b32 v53, v52 offset:8192
	ds_read2_b32 v[54:55], v31 offset0:128 offset1:160
	v_add_u32_e32 v56, v21, v24
	v_and_b32_e32 v57, 57, v56
	v_lshlrev_b32_e32 v58, 2, v57
	ds_read_b32 v59, v58 offset:8192
	v_add_u32_e32 v60, v22, v24
	v_and_b32_e32 v61, 62, v60
	v_lshlrev_b32_e32 v62, 2, v61
	ds_read_b32 v63, v62 offset:8192
	ds_read2_b32 v[64:65], v31 offset0:192 offset1:224
	v_add_u32_e32 v66, v23, v24
	v_and_b32_e32 v67, 59, v66
	v_lshlrev_b32_e32 v68, 2, v67
	ds_read_b32 v69, v68 offset:8192
	v_add_u32_e32 v24, v24, v17
	s_waitcnt lgkmcnt(0)
	v_fmac_f32_e32 v15, v33, v34
	v_fmac_f32_e32 v15, v39, v35
	v_fmac_f32_e32 v15, v43, v44
	v_fmac_f32_e32 v15, v49, v45
	v_fmac_f32_e32 v15, v53, v54
	v_fmac_f32_e32 v15, v59, v55
	v_fmac_f32_e32 v15, v63, v64
	v_fmac_f32_e32 v15, v69, v65
	s_cbranch_scc1 .LBB0_65
	v_or_b32_e32 v17, 6, v2
	v_add_u32_e32 v18, 48, v11
	v_add_u32_e32 v19, 12, v0
	v_add_u32_e32 v20, 18, v6
	v_add_u32_e32 v21, 24, v7
	v_add_u32_e32 v22, 30, v8
	v_add_u32_e32 v23, 36, v9
	v_add_u32_e32 v24, 42, v10
	v_mov_b32_e32 v16, 0
	v_mov_b32_e32 v25, 0
	s_mov_b32 s0, 0
.LBB0_67:
	v_and_b32_e32 v30, 48, v25
	v_lshlrev_b32_e32 v31, 2, v30
	v_add_u32_e32 v33, s0, v4
	ds_read_b32 v34, v31 offset:8192
	ds_read2_b32 v[36:37], v33 offset1:32
	s_addk_i32 s0, 0x400
	s_cmpk_lg_i32 s0, 0x2000
	v_add_u32_e32 v35, v17, v25
	v_and_b32_e32 v38, 62, v35
	v_lshlrev_b32_e32 v39, 2, v38
	ds_read_b32 v40, v39 offset:8192
	v_add_u32_e32 v41, v19, v25
	v_and_b32_e32 v42, 60, v41
	v_lshlrev_b32_e32 v43, 2, v42
	ds_read_b32 v44, v43 offset:8192
	ds_read2_b32 v[46:47], v33 offset0:64 offset1:96
	v_add_u32_e32 v45, v20, v25
	v_and_b32_e32 v48, 58, v45
	v_lshlrev_b32_e32 v49, 2, v48
	ds_read_b32 v50, v49 offset:8192
	v_add_u32_e32 v51, v21, v25
	v_and_b32_e32 v52, 56, v51
	v_lshlrev_b32_e32 v53, 2, v52
	ds_read_b32 v54, v53 offset:8192
	ds_read2_b32 v[56:57], v33 offset0:128 offset1:160
	v_add_u32_e32 v55, v22, v25
	v_and_b32_e32 v58, 62, v55
	v_lshlrev_b32_e32 v59, 2, v58
	ds_read_b32 v60, v59 offset:8192
	v_add_u32_e32 v61, v23, v25
	v_and_b32_e32 v62, 52, v61
	v_lshlrev_b32_e32 v63, 2, v62
	ds_read_b32 v64, v63 offset:8192
	ds_read2_b32 v[66:67], v33 offset0:192 offset1:224
	v_add_u32_e32 v65, v24, v25
	v_and_b32_e32 v68, 58, v65
	v_lshlrev_b32_e32 v69, 2, v68
	ds_read_b32 v70, v69 offset:8192
	v_add_u32_e32 v25, v25, v18
	s_waitcnt lgkmcnt(0)
	v_fmac_f32_e32 v16, v34, v36
	v_fmac_f32_e32 v16, v40, v37
	v_fmac_f32_e32 v16, v44, v46
	v_fmac_f32_e32 v16, v50, v47
	v_fmac_f32_e32 v16, v54, v56
	v_fmac_f32_e32 v16, v60, v57
	v_fmac_f32_e32 v16, v64, v66
	v_fmac_f32_e32 v16, v70, v67
	s_cbranch_scc1 .LBB0_67
	v_or_b32_e32 v17, 7, v2
	v_add_u32_e32 v11, 56, v11
	v_add_u32_e32 v18, 14, v0
	v_add_u32_e32 v6, 21, v6
	v_add_u32_e32 v7, 28, v7
	v_add_u32_e32 v8, 35, v8
	v_add_u32_e32 v9, 42, v9
	v_add_u32_e32 v10, 49, v10
	v_mov_b32_e32 v0, 0
	v_mov_b32_e32 v19, 0
	s_mov_b32 s0, 0
.LBB0_69:
	v_and_b32_e32 v24, 56, v19
	v_lshlrev_b32_e32 v25, 2, v24
	v_add_u32_e32 v26, s0, v4
	ds_read_b32 v27, v25 offset:8192
	ds_read2_b32 v[28:29], v26 offset1:32
	s_addk_i32 s0, 0x400
	s_cmpk_lg_i32 s0, 0x2000
	v_add_u32_e32 v30, v17, v19
	v_and_b32_e32 v31, 63, v30
	v_lshlrev_b32_e32 v33, 2, v31
	ds_read_b32 v34, v33 offset:8192
	v_add_u32_e32 v35, v18, v19
	v_and_b32_e32 v36, 62, v35
	v_lshlrev_b32_e32 v37, 2, v36
	ds_read_b32 v38, v37 offset:8192
	ds_read2_b32 v[40:41], v26 offset0:64 offset1:96
	v_add_u32_e32 v39, v6, v19
	v_and_b32_e32 v42, 61, v39
	v_lshlrev_b32_e32 v43, 2, v42
	ds_read_b32 v44, v43 offset:8192
	v_add_u32_e32 v45, v7, v19
	v_and_b32_e32 v46, 60, v45
	v_lshlrev_b32_e32 v47, 2, v46
	ds_read_b32 v48, v47 offset:8192
	ds_read2_b32 v[50:51], v26 offset0:128 offset1:160
	v_add_u32_e32 v49, v8, v19
	v_and_b32_e32 v52, 59, v49
	v_lshlrev_b32_e32 v53, 2, v52
	ds_read_b32 v54, v53 offset:8192
	v_add_u32_e32 v55, v9, v19
	v_and_b32_e32 v56, 58, v55
	v_lshlrev_b32_e32 v57, 2, v56
	ds_read_b32 v58, v57 offset:8192
	ds_read2_b32 v[60:61], v26 offset0:192 offset1:224
	v_add_u32_e32 v59, v10, v19
	v_and_b32_e32 v62, 57, v59
	v_lshlrev_b32_e32 v63, 2, v62
	ds_read_b32 v64, v63 offset:8192
	v_add_u32_e32 v19, v19, v11
	s_waitcnt lgkmcnt(0)
	v_fmac_f32_e32 v0, v27, v28
	v_fmac_f32_e32 v0, v34, v29
	v_fmac_f32_e32 v0, v38, v40
	v_fmac_f32_e32 v0, v44, v41
	v_fmac_f32_e32 v0, v48, v50
	v_fmac_f32_e32 v0, v54, v51
	v_fmac_f32_e32 v0, v58, v60
	v_fmac_f32_e32 v0, v64, v61
	s_cbranch_scc1 .LBB0_69
	v_bfe_u32 v9, v3, 16, 1
	v_and_b32_e32 v6, 56, v2
	v_add3_u32 v9, v3, v9, s80
	v_bfe_u32 v3, v5, 16, 1
	v_add3_u32 v3, v5, v3, s80
	v_and_b32_e32 v5, 0xffff0000, v3
	v_cvt_pk_bf16_f32 v3, v12, v13
	v_bfe_u32 v8, v0, 16, 1
	v_add3_u32 v0, v0, v8, s80
	v_and_b32_e32 v8, 0xffff0000, v0
	v_add_u32_e32 v0, s4, v1
	v_ashrrev_i32_e32 v1, 31, v0
	v_readlane_b32 s0, v253, 22
	v_lshlrev_b64 v[0:1], 10, v[0:1]
	v_readlane_b32 s1, v253, 23
	s_nop 1
	v_lshl_add_u64 v[0:1], s[0:1], 0, v[0:1]
	s_and_b32 s0, s3, 0x7fffff00
	s_lshl_b32 s78, s0, 1
	v_cvt_pk_bf16_f32 v4, v14, v15
	v_or_b32_sdwa v2, v5, v9 dst_sel:DWORD dst_unused:UNUSED_PAD src0_sel:DWORD src1_sel:WORD_1
	v_bfe_u32 v5, v16, 16, 1
	v_lshl_add_u64 v[0:1], v[0:1], 0, s[78:79]
	s_lshl_b32 s78, s2, 1
	v_lshl_add_u64 v[0:1], v[0:1], 0, s[78:79]
	v_lshlrev_b32_e32 v192, 1, v6
	v_add3_u32 v5, v16, v5, s80
	v_lshl_add_u64 v[0:1], v[0:1], 0, v[192:193]
	v_or_b32_sdwa v5, v8, v5 dst_sel:DWORD dst_unused:UNUSED_PAD src0_sel:DWORD src1_sel:WORD_1
	global_store_dwordx4 v[0:1], v[2:5], off
	s_barrier
	s_mov_b64 s[0:1], 0

.LBB0_1070:
	v_add_u32_e32 v29, s0, v5
	ds_read2_b32 v[30:31], v29 offset1:32
	v_add_u32_e32 v32, v2, v6
	v_add_u32_e32 v33, v0, v6
	v_and_b32_e32 v34, 56, v32
	v_and_b32_e32 v35, 48, v33
	ds_read2_b32 v[36:37], v29 offset0:64 offset1:96
	v_add_u32_e32 v38, v7, v6
	v_add_u32_e32 v39, v8, v6
	v_add_u32_e32 v40, v9, v6
	v_add_u32_e32 v41, v10, v6
	v_add_u32_e32 v42, v11, v6
	v_and_b32_e32 v43, 56, v38
	v_and_b32_e32 v44, 32, v39
	ds_read2_b32 v[46:47], v29 offset0:128 offset1:160
	v_and_b32_e32 v45, 56, v40
	v_and_b32_e32 v48, 48, v41
	v_and_b32_e32 v49, 56, v42
	v_lshlrev_b32_e32 v50, 2, v34
	v_lshlrev_b32_e32 v51, 2, v35
	v_lshlrev_b32_e32 v52, 2, v43
	v_lshlrev_b32_e32 v53, 2, v44
	v_lshlrev_b32_e32 v54, 2, v45
	v_lshlrev_b32_e32 v55, 2, v48
	v_lshlrev_b32_e32 v56, 2, v49
	ds_read2_b32 v[58:59], v29 offset0:192 offset1:224
	ds_read_b32 v57, v50 offset:8192
	ds_read_b32 v60, v51 offset:8192
	ds_read_b32 v61, v52 offset:8192
	ds_read_b32 v62, v53 offset:8192
	ds_read_b32 v63, v54 offset:8192
	ds_read_b32 v64, v55 offset:8192
	ds_read_b32 v65, v56 offset:8192
	s_addk_i32 s0, 0x400
	v_add_u32_e32 v6, v6, v12
	s_cmpk_eq_i32 s0, 0x2000
	s_waitcnt lgkmcnt(0)
	v_fmac_f32_e32 v3, v13, v30
	v_fmac_f32_e32 v3, v57, v31
	v_fmac_f32_e32 v3, v60, v36
	v_fmac_f32_e32 v3, v61, v37
	v_fmac_f32_e32 v3, v62, v46
	v_fmac_f32_e32 v3, v63, v47
	v_fmac_f32_e32 v3, v64, v58
	v_fmac_f32_e32 v3, v65, v59
	s_cbranch_scc0 .LBB0_1070
	v_or_b32_e32 v13, 1, v2
	v_add_u32_e32 v14, 8, v12
	v_add_u32_e32 v15, 2, v0
	v_add_u32_e32 v16, 3, v7
	v_add_u32_e32 v17, 4, v8
	v_add_u32_e32 v18, 5, v9
	v_add_u32_e32 v19, 6, v10
	v_add_u32_e32 v20, 7, v11
	v_mov_b32_e32 v6, 0
	v_mov_b32_e32 v21, 0
	s_mov_b32 s0, 0
.LBB0_1072:
	v_and_b32_e32 v38, 56, v21
	v_add_u32_e32 v39, s0, v5
	v_lshlrev_b32_e32 v40, 2, v38
	ds_read2_b32 v[42:43], v39 offset1:32
	v_add_u32_e32 v41, v13, v21
	v_add_u32_e32 v44, v15, v21
	v_add_u32_e32 v45, v16, v21
	v_add_u32_e32 v46, v17, v21
	v_add_u32_e32 v47, v18, v21
	v_add_u32_e32 v48, v19, v21
	v_add_u32_e32 v49, v20, v21
	v_and_b32_e32 v50, 57, v41
	v_and_b32_e32 v51, 58, v44
	ds_read2_b32 v[52:53], v39 offset0:64 offset1:96
	v_and_b32_e32 v54, 59, v45
	v_and_b32_e32 v55, 60, v46
	v_and_b32_e32 v56, 61, v47
	v_and_b32_e32 v57, 62, v48
	v_and_b32_e32 v58, 63, v49
	ds_read2_b32 v[60:61], v39 offset0:128 offset1:160
	v_lshlrev_b32_e32 v59, 2, v50
	v_lshlrev_b32_e32 v62, 2, v51
	v_lshlrev_b32_e32 v63, 2, v54
	v_lshlrev_b32_e32 v64, 2, v55
	v_lshlrev_b32_e32 v65, 2, v56
	v_lshlrev_b32_e32 v66, 2, v57
	v_lshlrev_b32_e32 v67, 2, v58
	ds_read2_b32 v[68:69], v39 offset0:192 offset1:224
	ds_read_b32 v70, v40 offset:8192
	ds_read_b32 v71, v59 offset:8192
	ds_read_b32 v72, v62 offset:8192
	ds_read_b32 v73, v63 offset:8192
	ds_read_b32 v74, v64 offset:8192
	ds_read_b32 v75, v65 offset:8192
	ds_read_b32 v76, v66 offset:8192
	ds_read_b32 v77, v67 offset:8192
	s_addk_i32 s0, 0x400
	v_add_u32_e32 v21, v21, v14
	s_cmpk_lg_i32 s0, 0x2000
	s_waitcnt lgkmcnt(0)
	v_fmac_f32_e32 v6, v70, v42
	v_fmac_f32_e32 v6, v71, v43
	v_fmac_f32_e32 v6, v72, v52
	v_fmac_f32_e32 v6, v73, v53
	v_fmac_f32_e32 v6, v74, v60
	v_fmac_f32_e32 v6, v75, v61
	v_fmac_f32_e32 v6, v76, v68
	v_fmac_f32_e32 v6, v77, v69
	s_cbranch_scc1 .LBB0_1072
	v_or_b32_e32 v14, 2, v2
	v_add_u32_e32 v15, 16, v12
	v_add_u32_e32 v16, 4, v0
	v_add_u32_e32 v17, 6, v7
	v_add_u32_e32 v18, 8, v8
	v_add_u32_e32 v19, 10, v9
	v_add_u32_e32 v20, 12, v10
	v_add_u32_e32 v21, 14, v11
	v_mov_b32_e32 v13, 0
	v_mov_b32_e32 v22, 0
	s_mov_b32 s0, 0
.LBB0_1074:
	v_add_u32_e32 v39, s0, v5
	ds_read2_b32 v[40:41], v39 offset1:32
	v_add_u32_e32 v42, v14, v22
	v_add_u32_e32 v43, v16, v22
	v_add_u32_e32 v44, v17, v22
	v_add_u32_e32 v45, v18, v22
	v_add_u32_e32 v46, v19, v22
	v_add_u32_e32 v47, v20, v22
	v_add_u32_e32 v48, v21, v22
	v_and_b32_e32 v49, 58, v42
	v_and_b32_e32 v50, 52, v43
	ds_read2_b32 v[52:53], v39 offset0:64 offset1:96
	v_and_b32_e32 v51, 48, v22
	v_and_b32_e32 v54, 62, v44
	v_and_b32_e32 v55, 56, v45
	v_and_b32_e32 v56, 58, v46
	v_and_b32_e32 v57, 60, v47
	v_and_b32_e32 v58, 62, v48
	v_lshlrev_b32_e32 v59, 2, v51
	ds_read2_b32 v[60:61], v39 offset0:128 offset1:160
	v_lshlrev_b32_e32 v62, 2, v49
	v_lshlrev_b32_e32 v63, 2, v50
	v_lshlrev_b32_e32 v64, 2, v54
	v_lshlrev_b32_e32 v65, 2, v55
	v_lshlrev_b32_e32 v66, 2, v56
	v_lshlrev_b32_e32 v67, 2, v57
	v_lshlrev_b32_e32 v68, 2, v58
	ds_read2_b32 v[70:71], v39 offset0:192 offset1:224
	ds_read_b32 v69, v59 offset:8192
	ds_read_b32 v72, v62 offset:8192
	ds_read_b32 v73, v63 offset:8192
	ds_read_b32 v74, v64 offset:8192
	ds_read_b32 v75, v65 offset:8192
	ds_read_b32 v76, v66 offset:8192
	ds_read_b32 v77, v67 offset:8192
	ds_read_b32 v78, v68 offset:8192
	s_addk_i32 s0, 0x400
	v_add_u32_e32 v22, v22, v15
	s_cmpk_lg_i32 s0, 0x2000
	s_waitcnt lgkmcnt(0)
	v_fmac_f32_e32 v13, v69, v40
	v_fmac_f32_e32 v13, v72, v41
	v_fmac_f32_e32 v13, v73, v52
	v_fmac_f32_e32 v13, v74, v53
	v_fmac_f32_e32 v13, v75, v60
	v_fmac_f32_e32 v13, v76, v61
	v_fmac_f32_e32 v13, v77, v70
	v_fmac_f32_e32 v13, v78, v71
	s_cbranch_scc1 .LBB0_1074
	v_or_b32_e32 v15, 3, v2
	v_add_u32_e32 v16, 24, v12
	v_add_u32_e32 v17, 6, v0
	v_add_u32_e32 v18, 9, v7
	v_add_u32_e32 v19, 12, v8
	v_add_u32_e32 v20, 15, v9
	v_add_u32_e32 v21, 18, v10
	v_add_u32_e32 v22, 21, v11
	v_mov_b32_e32 v14, 0
	v_mov_b32_e32 v23, 0
	s_mov_b32 s0, 0
.LBB0_1076:
	v_and_b32_e32 v40, 56, v23
	v_add_u32_e32 v41, s0, v5
	v_lshlrev_b32_e32 v42, 2, v40
	ds_read2_b32 v[44:45], v41 offset1:32
	v_add_u32_e32 v43, v15, v23
	v_add_u32_e32 v46, v17, v23
	v_add_u32_e32 v47, v18, v23
	v_add_u32_e32 v48, v19, v23
	v_add_u32_e32 v49, v20, v23
	v_add_u32_e32 v50, v21, v23
	v_add_u32_e32 v51, v22, v23
	v_and_b32_e32 v52, 59, v43
	v_and_b32_e32 v53, 62, v46
	ds_read2_b32 v[54:55], v41 offset0:64 offset1:96
	v_and_b32_e32 v56, 57, v47
	v_and_b32_e32 v57, 60, v48
	v_and_b32_e32 v58, 63, v49
	v_and_b32_e32 v59, 58, v50
	v_and_b32_e32 v60, 61, v51
	ds_read2_b32 v[62:63], v41 offset0:128 offset1:160
	v_lshlrev_b32_e32 v61, 2, v52
	v_lshlrev_b32_e32 v64, 2, v53
	v_lshlrev_b32_e32 v65, 2, v56
	v_lshlrev_b32_e32 v66, 2, v57
	v_lshlrev_b32_e32 v67, 2, v58
	v_lshlrev_b32_e32 v68, 2, v59
	v_lshlrev_b32_e32 v69, 2, v60
	ds_read2_b32 v[70:71], v41 offset0:192 offset1:224
	ds_read_b32 v72, v42 offset:8192
	ds_read_b32 v73, v61 offset:8192
	ds_read_b32 v74, v64 offset:8192
	ds_read_b32 v75, v65 offset:8192
	ds_read_b32 v76, v66 offset:8192
	ds_read_b32 v77, v67 offset:8192
	ds_read_b32 v78, v68 offset:8192
	ds_read_b32 v79, v69 offset:8192
	s_addk_i32 s0, 0x400
	v_add_u32_e32 v23, v23, v16
	s_cmpk_lg_i32 s0, 0x2000
	s_waitcnt lgkmcnt(0)
	v_fmac_f32_e32 v14, v72, v44
	v_fmac_f32_e32 v14, v73, v45
	v_fmac_f32_e32 v14, v74, v54
	v_fmac_f32_e32 v14, v75, v55
	v_fmac_f32_e32 v14, v76, v62
	v_fmac_f32_e32 v14, v77, v63
	v_fmac_f32_e32 v14, v78, v70
	v_fmac_f32_e32 v14, v79, v71
	s_cbranch_scc1 .LBB0_1076
	v_or_b32_e32 v16, 4, v2
	v_add_u32_e32 v17, 32, v12
	v_add_u32_e32 v18, 8, v0
	v_add_u32_e32 v19, 12, v7
	v_add_u32_e32 v20, 16, v8
	v_add_u32_e32 v21, 20, v9
	v_add_u32_e32 v22, 24, v10
	v_add_u32_e32 v23, 28, v11
	v_mov_b32_e32 v15, 0
	v_mov_b32_e32 v24, 0
	s_mov_b32 s0, 0
.LBB0_1078:
	v_add_u32_e32 v41, s0, v5
	ds_read2_b32 v[42:43], v41 offset1:32
	v_add_u32_e32 v44, v16, v24
	v_add_u32_e32 v45, v18, v24
	v_add_u32_e32 v46, v19, v24
	v_add_u32_e32 v47, v20, v24
	v_add_u32_e32 v48, v21, v24
	v_add_u32_e32 v49, v22, v24
	v_add_u32_e32 v50, v23, v24
	v_and_b32_e32 v51, 60, v44
	v_and_b32_e32 v52, 56, v45
	ds_read2_b32 v[54:55], v41 offset0:64 offset1:96
	v_and_b32_e32 v53, 32, v24
	v_and_b32_e32 v56, 60, v46
	v_and_b32_e32 v57, 48, v47
	v_and_b32_e32 v58, 60, v48
	v_and_b32_e32 v59, 56, v49
	v_and_b32_e32 v60, 60, v50
	v_lshlrev_b32_e32 v61, 2, v53
	ds_read2_b32 v[62:63], v41 offset0:128 offset1:160
	v_lshlrev_b32_e32 v64, 2, v51
	v_lshlrev_b32_e32 v65, 2, v52
	v_lshlrev_b32_e32 v66, 2, v56
	v_lshlrev_b32_e32 v67, 2, v57
	v_lshlrev_b32_e32 v68, 2, v58
	v_lshlrev_b32_e32 v69, 2, v59
	v_lshlrev_b32_e32 v70, 2, v60
	ds_read2_b32 v[72:73], v41 offset0:192 offset1:224
	ds_read_b32 v71, v61 offset:8192
	ds_read_b32 v74, v64 offset:8192
	ds_read_b32 v75, v65 offset:8192
	ds_read_b32 v76, v66 offset:8192
	ds_read_b32 v77, v67 offset:8192
	ds_read_b32 v78, v68 offset:8192
	ds_read_b32 v79, v69 offset:8192
	ds_read_b32 v84, v70 offset:8192
	s_addk_i32 s0, 0x400
	v_add_u32_e32 v24, v24, v17
	s_cmpk_lg_i32 s0, 0x2000
	s_waitcnt lgkmcnt(0)
	v_fmac_f32_e32 v15, v71, v42
	v_fmac_f32_e32 v15, v74, v43
	v_fmac_f32_e32 v15, v75, v54
	v_fmac_f32_e32 v15, v76, v55
	v_fmac_f32_e32 v15, v77, v62
	v_fmac_f32_e32 v15, v78, v63
	v_fmac_f32_e32 v15, v79, v72
	v_fmac_f32_e32 v15, v84, v73
	s_cbranch_scc1 .LBB0_1078
	v_or_b32_e32 v17, 5, v2
	v_add_u32_e32 v18, 40, v12
	v_add_u32_e32 v19, 10, v0
	v_add_u32_e32 v20, 15, v7
	v_add_u32_e32 v21, 20, v8
	v_add_u32_e32 v22, 25, v9
	v_add_u32_e32 v23, 30, v10
	v_add_u32_e32 v24, 35, v11
	v_mov_b32_e32 v16, 0
	v_mov_b32_e32 v25, 0
	s_mov_b32 s0, 0
.LBB0_1080:
	v_and_b32_e32 v42, 56, v25
	v_add_u32_e32 v43, s0, v5
	v_lshlrev_b32_e32 v44, 2, v42
	ds_read2_b32 v[46:47], v43 offset1:32
	v_add_u32_e32 v45, v17, v25
	v_add_u32_e32 v48, v19, v25
	v_add_u32_e32 v49, v20, v25
	v_add_u32_e32 v50, v21, v25
	v_add_u32_e32 v51, v22, v25
	v_add_u32_e32 v52, v23, v25
	v_add_u32_e32 v53, v24, v25
	v_and_b32_e32 v54, 61, v45
	v_and_b32_e32 v55, 58, v48
	ds_read2_b32 v[56:57], v43 offset0:64 offset1:96
	v_and_b32_e32 v58, 63, v49
	v_and_b32_e32 v59, 60, v50
	v_and_b32_e32 v60, 57, v51
	v_and_b32_e32 v61, 62, v52
	v_and_b32_e32 v62, 59, v53
	ds_read2_b32 v[64:65], v43 offset0:128 offset1:160
	v_lshlrev_b32_e32 v63, 2, v54
	v_lshlrev_b32_e32 v66, 2, v55
	v_lshlrev_b32_e32 v67, 2, v58
	v_lshlrev_b32_e32 v68, 2, v59
	v_lshlrev_b32_e32 v69, 2, v60
	v_lshlrev_b32_e32 v70, 2, v61
	v_lshlrev_b32_e32 v71, 2, v62
	ds_read2_b32 v[72:73], v43 offset0:192 offset1:224
	ds_read_b32 v74, v44 offset:8192
	ds_read_b32 v75, v63 offset:8192
	ds_read_b32 v76, v66 offset:8192
	ds_read_b32 v77, v67 offset:8192
	ds_read_b32 v78, v68 offset:8192
	ds_read_b32 v79, v69 offset:8192
	ds_read_b32 v84, v70 offset:8192
	ds_read_b32 v85, v71 offset:8192
	s_addk_i32 s0, 0x400
	v_add_u32_e32 v25, v25, v18
	s_cmpk_lg_i32 s0, 0x2000
	s_waitcnt lgkmcnt(0)
	v_fmac_f32_e32 v16, v74, v46
	v_fmac_f32_e32 v16, v75, v47
	v_fmac_f32_e32 v16, v76, v56
	v_fmac_f32_e32 v16, v77, v57
	v_fmac_f32_e32 v16, v78, v64
	v_fmac_f32_e32 v16, v79, v65
	v_fmac_f32_e32 v16, v84, v72
	v_fmac_f32_e32 v16, v85, v73
	s_cbranch_scc1 .LBB0_1080
	v_or_b32_e32 v18, 6, v2
	v_add_u32_e32 v19, 48, v12
	v_add_u32_e32 v20, 12, v0
	v_add_u32_e32 v21, 18, v7
	v_add_u32_e32 v22, 24, v8
	v_add_u32_e32 v23, 30, v9
	v_add_u32_e32 v24, 36, v10
	v_add_u32_e32 v25, 42, v11
	v_mov_b32_e32 v17, 0
	v_mov_b32_e32 v26, 0
	s_mov_b32 s0, 0
.LBB0_1082:
	v_add_u32_e32 v43, s0, v5
	ds_read2_b32 v[44:45], v43 offset1:32
	v_add_u32_e32 v46, v18, v26
	v_add_u32_e32 v47, v20, v26
	v_add_u32_e32 v48, v21, v26
	v_add_u32_e32 v49, v22, v26
	v_add_u32_e32 v50, v23, v26
	v_add_u32_e32 v51, v24, v26
	v_add_u32_e32 v52, v25, v26
	v_and_b32_e32 v53, 62, v46
	v_and_b32_e32 v54, 60, v47
	ds_read2_b32 v[56:57], v43 offset0:64 offset1:96
	v_and_b32_e32 v55, 48, v26
	v_and_b32_e32 v58, 58, v48
	v_and_b32_e32 v59, 56, v49
	v_and_b32_e32 v60, 62, v50
	v_and_b32_e32 v61, 52, v51
	v_and_b32_e32 v62, 58, v52
	v_lshlrev_b32_e32 v63, 2, v55
	ds_read2_b32 v[64:65], v43 offset0:128 offset1:160
	v_lshlrev_b32_e32 v66, 2, v53
	v_lshlrev_b32_e32 v67, 2, v54
	v_lshlrev_b32_e32 v68, 2, v58
	v_lshlrev_b32_e32 v69, 2, v59
	v_lshlrev_b32_e32 v70, 2, v60
	v_lshlrev_b32_e32 v71, 2, v61
	v_lshlrev_b32_e32 v72, 2, v62
	ds_read2_b32 v[74:75], v43 offset0:192 offset1:224
	ds_read_b32 v73, v63 offset:8192
	ds_read_b32 v76, v66 offset:8192
	ds_read_b32 v77, v67 offset:8192
	ds_read_b32 v78, v68 offset:8192
	ds_read_b32 v79, v69 offset:8192
	ds_read_b32 v84, v70 offset:8192
	ds_read_b32 v85, v71 offset:8192
	ds_read_b32 v86, v72 offset:8192
	s_addk_i32 s0, 0x400
	v_add_u32_e32 v26, v26, v19
	s_cmpk_lg_i32 s0, 0x2000
	s_waitcnt lgkmcnt(0)
	v_fmac_f32_e32 v17, v73, v44
	v_fmac_f32_e32 v17, v76, v45
	v_fmac_f32_e32 v17, v77, v56
	v_fmac_f32_e32 v17, v78, v57
	v_fmac_f32_e32 v17, v79, v64
	v_fmac_f32_e32 v17, v84, v65
	v_fmac_f32_e32 v17, v85, v74
	v_fmac_f32_e32 v17, v86, v75
	s_cbranch_scc1 .LBB0_1082
	v_or_b32_e32 v18, 7, v2
	v_add_u32_e32 v12, 56, v12
	v_add_u32_e32 v19, 14, v0
	v_add_u32_e32 v7, 21, v7
	v_add_u32_e32 v8, 28, v8
	v_add_u32_e32 v9, 35, v9
	v_add_u32_e32 v10, 42, v10
	v_add_u32_e32 v11, 49, v11
	v_mov_b32_e32 v0, 0
	v_mov_b32_e32 v20, 0
	s_mov_b32 s0, 0
.LBB0_1084:
	v_add_u32_e32 v37, s0, v5
	ds_read2_b32 v[38:39], v37 offset1:32
	v_add_u32_e32 v40, v18, v20
	v_add_u32_e32 v41, v19, v20
	v_add_u32_e32 v42, v7, v20
	v_add_u32_e32 v43, v8, v20
	v_add_u32_e32 v44, v9, v20
	v_add_u32_e32 v45, v10, v20
	v_add_u32_e32 v46, v11, v20
	v_and_b32_e32 v47, 63, v40
	v_and_b32_e32 v48, 62, v41
	ds_read2_b32 v[50:51], v37 offset0:64 offset1:96
	v_and_b32_e32 v49, 56, v20
	v_and_b32_e32 v52, 61, v42
	v_and_b32_e32 v53, 60, v43
	v_and_b32_e32 v54, 59, v44
	v_and_b32_e32 v55, 58, v45
	v_and_b32_e32 v56, 57, v46
	v_lshlrev_b32_e32 v57, 2, v49
	ds_read2_b32 v[58:59], v37 offset0:128 offset1:160
	v_lshlrev_b32_e32 v60, 2, v47
	v_lshlrev_b32_e32 v61, 2, v48
	v_lshlrev_b32_e32 v62, 2, v52
	v_lshlrev_b32_e32 v63, 2, v53
	v_lshlrev_b32_e32 v64, 2, v54
	v_lshlrev_b32_e32 v65, 2, v55
	v_lshlrev_b32_e32 v66, 2, v56
	ds_read2_b32 v[68:69], v37 offset0:192 offset1:224
	ds_read_b32 v67, v57 offset:8192
	ds_read_b32 v70, v60 offset:8192
	ds_read_b32 v71, v61 offset:8192
	ds_read_b32 v72, v62 offset:8192
	ds_read_b32 v73, v63 offset:8192
	ds_read_b32 v74, v64 offset:8192
	ds_read_b32 v75, v65 offset:8192
	ds_read_b32 v76, v66 offset:8192
	s_addk_i32 s0, 0x400
	v_add_u32_e32 v20, v20, v12
	s_cmpk_lg_i32 s0, 0x2000
	s_waitcnt lgkmcnt(0)
	v_fmac_f32_e32 v0, v67, v38
	v_fmac_f32_e32 v0, v70, v39
	v_fmac_f32_e32 v0, v71, v50
	v_fmac_f32_e32 v0, v72, v51
	v_fmac_f32_e32 v0, v73, v58
	v_fmac_f32_e32 v0, v74, v59
	v_fmac_f32_e32 v0, v75, v68
	v_fmac_f32_e32 v0, v76, v69
	s_cbranch_scc1 .LBB0_1084
	v_cvt_pk_bf16_f32 v7, v13, v14
	v_cvt_pk_bf16_f32 v9, v17, v0
	v_add_u32_e32 v0, s4, v1
	v_cvt_pk_bf16_f32 v6, v3, v6
	v_ashrrev_i32_e32 v1, 31, v0
	v_readlane_b32 s0, v253, 22
	v_lshlrev_b64 v[0:1], 10, v[0:1]
	v_readlane_b32 s1, v253, 23
	s_nop 1
	v_lshl_add_u64 v[0:1], s[0:1], 0, v[0:1]
	s_and_b32 s0, s3, 0x7fffff00
	s_lshl_b32 s78, s0, 1
	v_and_b32_e32 v2, 56, v2
	v_cvt_pk_bf16_f32 v8, v15, v16
	v_lshl_add_u64 v[0:1], v[0:1], 0, s[78:79]
	s_lshl_b32 s78, s2, 1
	v_lshl_add_u64 v[0:1], v[0:1], 0, s[78:79]
	v_lshlrev_b32_e32 v192, 1, v2
	v_lshl_add_u64 v[0:1], v[0:1], 0, v[192:193]
	global_store_dwordx4 v[0:1], v[6:9], off
	s_barrier
	s_mov_b64 s[0:1], 0
